# attention row-max as two interleaved max3 chains; cross-half max exchange via v_permlane32_swap instead of ds_bpermute
# speedup vs baseline: 1.0025x; 1.0025x over previous
.LBB0_220:
	s_nop 10
	v_max3_f32 v1, v96, v97, v98
	v_max3_f32 v3, v80, v81, v82
	v_max3_f32 v1, v1, v99, v100
	v_max3_f32 v3, v3, v83, v84
	v_max3_f32 v1, v1, v101, v102
	v_max3_f32 v3, v3, v85, v86
	v_max3_f32 v1, v1, v103, v104
	v_max3_f32 v3, v3, v87, v88
	v_max3_f32 v1, v1, v105, v106
	v_max3_f32 v3, v3, v89, v90
	v_max3_f32 v1, v1, v107, v108
	v_max3_f32 v3, v3, v91, v92
	v_max3_f32 v1, v1, v109, v110
	v_max3_f32 v3, v3, v93, v94
	v_max_f32_e32 v1, v1, v111
	v_max_f32_e32 v3, v3, v95
	v_max_f32_e32 v1, v1, v3
	v_mov_b32_e32 v3, v1
	s_xor_b64 s[64:65], s[64:65], -1
	s_and_b64 vcc, exec, s[64:65]
	s_waitcnt lgkmcnt(0)
	v_permlane32_swap_b32 v3, v1
	v_max_f32_e32 v1, v1, v3
	s_cbranch_vccz .LBB0_234
	s_mov_b32 s17, 0x41000000
	v_cmp_lt_f32_e32 vcc, s17, v1
	s_mov_b64 s[66:67], 0
	s_mov_b64 s[64:65], 0
	s_cbranch_vccz .LBB0_223
	v_max_f32_e32 v3, v1, v1
	v_max_f32_e32 v4, 0, v3
	s_mov_b64 s[64:65], -1
